# samp_hg: skip the state prefetch of a never-processed unit in a workgroup's last iteration (saves 16.8 MB of reads per layer), on top of v5
# baseline (speedup 1.0000x reference)
.LBB0_562:
	s_ashr_i32 s8, s9, 2
	s_and_b32 s9, s9, -4
	v_add_u32_e32 v74, s9, v83
	v_mov_b64_e32 v[78:79], s[4:5]
	v_mad_i64_i32 v[78:79], s[14:15], v74, s89, v[78:79]
	s_lshl_b32 s54, s13, 1
	v_lshl_add_u64 v[78:79], v[78:79], 0, s[54:55]
	v_lshl_add_u64 v[78:79], v[78:79], 0, v[208:209]
	global_load_ushort v198, v[78:79], off offset:2048
	s_movk_i32 s13, 0x1000
	s_ashr_i32 s9, s8, 31
	s_lshl_b64 s[8:9], s[8:9], 2
	s_add_u32 s8, s8, s52
	s_addc_u32 s9, s9, s53
	s_or_b32 s8, s8, s12
	s_lshl_b64 s[8:9], s[8:9], 16
	global_load_ushort v199, v[78:79], off offset:1024
	global_load_ushort v200, v[78:79], off offset:3072
	v_add_co_u32_e32 v78, vcc, s13, v78
	s_nop 1
	v_addc_co_u32_e32 v79, vcc, 0, v79, vcc
	global_load_ushort v75, v[78:79], off
	global_load_dword v77, v[66:67], off
	s_cmpk_gt_i32 s1, 0x1ff
	s_cbranch_scc1 .Lshg_nopf
	s_movk_i32 s98, 0x1000
	v_add_co_u32_e32 v16, vcc, s98, v24
	global_load_dword v0, v[24:25], off
	global_load_dword v1, v[24:25], off offset:512
	global_load_dword v2, v[24:25], off offset:1024
	global_load_dword v3, v[24:25], off offset:1536
	global_load_dword v4, v[24:25], off offset:2048
	global_load_dword v5, v[24:25], off offset:2560
	global_load_dword v6, v[24:25], off offset:3072
	global_load_dword v7, v[24:25], off offset:3584
	v_addc_co_u32_e32 v17, vcc, 0, v25, vcc
	v_add_co_u32_e32 v26, vcc, s70, v24
	s_movk_i32 s98, 0x3000
	s_nop 0
	v_addc_co_u32_e32 v27, vcc, 0, v25, vcc
	global_load_dword v8, v[26:27], off offset:-4096
	global_load_dword v9, v[16:17], off offset:512
	global_load_dword v10, v[16:17], off offset:1024
	global_load_dword v11, v[16:17], off offset:1536
	global_load_dword v12, v[16:17], off offset:2048
	global_load_dword v13, v[16:17], off offset:2560
	global_load_dword v14, v[16:17], off offset:3072
	global_load_dword v15, v[16:17], off offset:3584
	s_nop 0
	global_load_dword v16, v[26:27], off
	global_load_dword v17, v[26:27], off offset:512
	global_load_dword v18, v[26:27], off offset:1024
	global_load_dword v19, v[26:27], off offset:1536
	global_load_dword v20, v[26:27], off offset:2048
	global_load_dword v21, v[26:27], off offset:2560
	global_load_dword v22, v[26:27], off offset:3072
	global_load_dword v23, v[26:27], off offset:3584
	v_add_co_u32_e32 v210, vcc, s98, v24
	s_nop 1
	v_addc_co_u32_e32 v211, vcc, 0, v25, vcc
	global_load_dword v24, v[210:211], off
	global_load_dword v25, v[210:211], off offset:512
	global_load_dword v26, v[210:211], off offset:1024
	global_load_dword v27, v[210:211], off offset:1536
	global_load_dword v28, v[210:211], off offset:2048
	global_load_dword v29, v[210:211], off offset:2560
	global_load_dword v30, v[210:211], off offset:3072
	global_load_dword v31, v[210:211], off offset:3584
	s_waitcnt vmcnt(34)
	s_branch .Lshg_join

.Lshg_join:
	v_lshlrev_b32_e32 v87, 16, v198
	v_lshlrev_b32_e32 v88, 16, v199
	v_lshlrev_b32_e32 v89, 16, v200
	v_mul_f32_e32 v78, 0xbfb8aa3b, v87
	v_exp_f32_e32 v78, v78
	v_sub_f32_e32 v87, 1.0, v76
	s_barrier
	v_add_f32_e32 v79, 1.0, v78
	v_rcp_f32_e32 v79, v79
	v_mul_f32_e32 v78, v87, v78
	v_fmac_f32_e32 v76, v87, v79
	v_mul_f32_e32 v78, v78, v79
	ds_write2st64_b32 v84, v76, v78 offset1:8
	ds_write2st64_b32 v84, v88, v89 offset0:16 offset1:24
	s_waitcnt lgkmcnt(0)
	s_barrier
	ds_read2st64_b32 v[78:79], v82 offset0:24 offset1:26
	ds_read_b128 v[88:91], v68
	ds_read_b128 v[100:103], v68 offset:16
	ds_read_b128 v[104:107], v68 offset:32
	ds_read_b128 v[108:111], v68 offset:48
	ds_read_b128 v[92:95], v68 offset:2048
	ds_read_b128 v[112:115], v68 offset:4096
	s_waitcnt lgkmcnt(1)
	v_mul_f32_e32 v98, v78, v92
	v_mul_f32_e32 v92, v78, v93
	v_mul_f32_e32 v93, v78, v94
	v_mul_f32_e32 v94, v78, v95
	v_fmac_f32_e32 v98, v32, v88
	v_fmac_f32_e32 v92, v33, v89
	v_fmac_f32_e32 v93, v34, v90
	v_fmac_f32_e32 v94, v35, v91
	ds_read_b128 v[88:91], v68 offset:2064
	s_waitcnt lgkmcnt(1)
	v_fma_f32 v32, v112, v98, 0
	v_fmac_f32_e32 v32, v113, v92
	v_fmac_f32_e32 v32, v114, v93
	v_fmac_f32_e32 v32, v115, v94
	ds_read_b128 v[112:115], v68 offset:4112
	s_waitcnt lgkmcnt(1)
	v_mul_f32_e32 v97, v78, v88
	v_mul_f32_e32 v88, v78, v89
	v_fmac_f32_e32 v97, v36, v100
	v_fmac_f32_e32 v88, v37, v101
	ds_read_b128 v[34:37], v68 offset:2080
	v_mul_f32_e32 v87, v78, v90
	v_mul_f32_e32 v76, v78, v91
	v_fmac_f32_e32 v87, v38, v102
	v_fmac_f32_e32 v76, v39, v103
	ds_read_b128 v[100:103], v68 offset:4128
	s_waitcnt lgkmcnt(2)
	v_fmac_f32_e32 v32, v112, v97
	v_fmac_f32_e32 v32, v113, v88
	v_fmac_f32_e32 v32, v114, v87
	s_waitcnt lgkmcnt(1)
	v_mul_f32_e32 v96, v78, v34
	v_fmac_f32_e32 v32, v115, v76
	v_fmac_f32_e32 v96, v40, v104
	v_mul_f32_e32 v89, v78, v35
	v_fmac_f32_e32 v89, v41, v105
	v_mul_f32_e32 v90, v78, v36
	ds_read_b128 v[38:41], v68 offset:2096
	s_waitcnt lgkmcnt(1)
	v_fmac_f32_e32 v32, v100, v96
	v_fmac_f32_e32 v32, v101, v89
	v_fmac_f32_e32 v90, v42, v106
	v_mul_f32_e32 v91, v78, v37
	v_fmac_f32_e32 v32, v102, v90
	v_fmac_f32_e32 v91, v43, v107
	v_fmac_f32_e32 v32, v103, v91
	ds_read_b128 v[100:103], v68 offset:4144
	s_waitcnt lgkmcnt(1)
	v_mul_f32_e32 v95, v78, v38
	v_fmac_f32_e32 v95, v44, v108
	v_mul_f32_e32 v38, v78, v39
	v_fmac_f32_e32 v38, v45, v109
	s_waitcnt lgkmcnt(0)
	v_fmac_f32_e32 v32, v100, v95
	v_mul_f32_e32 v37, v78, v40
	v_mul_f32_e32 v36, v78, v41
	v_fmac_f32_e32 v32, v101, v38
	v_fmac_f32_e32 v37, v46, v110
	v_fmac_f32_e32 v36, v47, v111
	ds_read_b128 v[40:43], v68 offset:64
	ds_read_b128 v[44:47], v68 offset:2112
	v_fmac_f32_e32 v32, v102, v37
	v_fmac_f32_e32 v32, v103, v36
	ds_read_b128 v[100:103], v68 offset:4160
	s_waitcnt lgkmcnt(1)
	v_mul_f32_e32 v44, v78, v44
	v_fmac_f32_e32 v44, v48, v40
	v_mul_f32_e32 v39, v78, v45
	s_waitcnt lgkmcnt(0)
	v_fmac_f32_e32 v32, v100, v44
	v_fmac_f32_e32 v39, v49, v41
	v_mul_f32_e32 v40, v78, v46
	v_fmac_f32_e32 v32, v101, v39
	v_fmac_f32_e32 v40, v50, v42
	v_mul_f32_e32 v41, v78, v47
	v_fmac_f32_e32 v32, v102, v40
	v_fmac_f32_e32 v41, v51, v43
	v_fmac_f32_e32 v32, v103, v41
	ds_read_b128 v[46:49], v68 offset:80
	ds_read_b128 v[100:103], v68 offset:2128
	ds_read_b128 v[104:107], v68 offset:4176
	s_waitcnt lgkmcnt(1)
	v_mul_f32_e32 v45, v78, v100
	v_fmac_f32_e32 v45, v52, v46
	v_mul_f32_e32 v42, v78, v101
	v_mul_f32_e32 v43, v78, v102
	v_mul_f32_e32 v46, v78, v103
	v_fmac_f32_e32 v42, v53, v47
	v_fmac_f32_e32 v43, v54, v48
	v_fmac_f32_e32 v46, v55, v49
	ds_read_b128 v[48:51], v68 offset:96
	ds_read_b128 v[52:55], v68 offset:2144
	ds_read_b128 v[100:103], v68 offset:4192
	s_waitcnt lgkmcnt(3)
	v_fmac_f32_e32 v32, v104, v45
	v_fmac_f32_e32 v32, v105, v42
	v_fmac_f32_e32 v32, v106, v43
	s_waitcnt lgkmcnt(1)
	v_mul_f32_e32 v47, v78, v52
	v_fmac_f32_e32 v32, v107, v46
	v_fmac_f32_e32 v47, v56, v48
	v_mul_f32_e32 v99, v78, v53
	s_waitcnt lgkmcnt(0)
	v_fmac_f32_e32 v32, v100, v47
	v_fmac_f32_e32 v99, v57, v49
	v_fmac_f32_e32 v32, v101, v99
	v_mul_f32_e32 v100, v78, v54
	v_mul_f32_e32 v101, v78, v55
	v_fmac_f32_e32 v100, v58, v50
	v_fmac_f32_e32 v101, v59, v51
	ds_read_b128 v[52:55], v68 offset:112
	ds_read_b128 v[56:59], v68 offset:2160
	ds_read_b128 v[104:107], v68 offset:4208
	v_fmac_f32_e32 v32, v102, v100
	v_fmac_f32_e32 v32, v103, v101
	s_waitcnt lgkmcnt(1)
	v_mul_f32_e32 v102, v78, v56
	v_fmac_f32_e32 v102, v60, v52
	v_mul_f32_e32 v51, v78, v57
	s_waitcnt lgkmcnt(0)
	v_fmac_f32_e32 v32, v104, v102
	v_fmac_f32_e32 v51, v61, v53
	v_mul_f32_e32 v52, v78, v58
	v_fmac_f32_e32 v32, v105, v51
	v_fmac_f32_e32 v52, v62, v54
	v_mul_f32_e32 v53, v78, v59
	v_fmac_f32_e32 v32, v106, v52
	v_fmac_f32_e32 v53, v63, v55
	v_fmac_f32_e32 v32, v107, v53
	ds_write_b32 v86, v32 offset:8192
	ds_read_b128 v[56:59], v68 offset:512
	ds_read_b128 v[60:63], v68 offset:528
	ds_read_b128 v[104:107], v68 offset:544
	ds_read_b128 v[32:35], v68 offset:560
	ds_read_b128 v[108:111], v68 offset:2560
	ds_read_b128 v[112:115], v68 offset:4608
	s_waitcnt lgkmcnt(1)
	v_mul_f32_e32 v54, v79, v108
	v_mul_f32_e32 v55, v79, v109
	v_fmac_f32_e32 v54, v98, v56
	v_fmac_f32_e32 v55, v92, v57
	v_mul_f32_e32 v56, v79, v110
	v_mul_f32_e32 v57, v79, v111
	ds_read_b128 v[108:111], v68 offset:2576
	s_waitcnt lgkmcnt(1)
	v_fma_f32 v98, v112, v54, 0
	v_fmac_f32_e32 v98, v113, v55
	v_fmac_f32_e32 v56, v93, v58
	v_fmac_f32_e32 v98, v114, v56
	v_fmac_f32_e32 v57, v94, v59
	s_waitcnt lgkmcnt(0)
	v_mul_f32_e32 v58, v79, v108
	v_mul_f32_e32 v48, v79, v109
	v_mul_f32_e32 v49, v79, v110
	v_mul_f32_e32 v59, v79, v111
	v_fmac_f32_e32 v98, v115, v57
	v_fmac_f32_e32 v58, v97, v60
	ds_read_b128 v[112:115], v68 offset:4624
	v_fmac_f32_e32 v48, v88, v61
	v_fmac_f32_e32 v49, v87, v62
	v_fmac_f32_e32 v59, v76, v63
	ds_read_b128 v[60:63], v68 offset:2592
	ds_read_b128 v[108:111], v68 offset:4640
	s_waitcnt lgkmcnt(2)
	v_fmac_f32_e32 v98, v112, v58
	v_fmac_f32_e32 v98, v113, v48
	v_fmac_f32_e32 v98, v114, v49
	s_waitcnt lgkmcnt(1)
	v_mul_f32_e32 v61, v79, v61
	v_mul_f32_e32 v62, v79, v62
	v_mul_f32_e32 v63, v79, v63
	v_fmac_f32_e32 v61, v89, v105
	v_fmac_f32_e32 v62, v90, v106
	v_fmac_f32_e32 v63, v91, v107
	ds_read_b128 v[88:91], v68 offset:2608
	v_mul_f32_e32 v60, v79, v60
	v_fmac_f32_e32 v98, v115, v59
	v_fmac_f32_e32 v60, v96, v104
	s_waitcnt lgkmcnt(1)
	v_fmac_f32_e32 v98, v108, v60
	s_waitcnt lgkmcnt(0)
	v_mul_f32_e32 v76, v79, v88
	v_fmac_f32_e32 v76, v95, v32
	ds_read_b128 v[92:95], v68 offset:4656
	v_fmac_f32_e32 v98, v109, v61
	v_fmac_f32_e32 v98, v110, v62
	v_fmac_f32_e32 v98, v111, v63
	v_mul_f32_e32 v50, v79, v89
	s_waitcnt lgkmcnt(0)
	v_fmac_f32_e32 v98, v92, v76
	v_fmac_f32_e32 v50, v38, v33
	v_mul_f32_e32 v38, v79, v90
	v_mul_f32_e32 v78, v79, v91
	v_fmac_f32_e32 v98, v93, v50
	v_fmac_f32_e32 v38, v37, v34
	v_fmac_f32_e32 v78, v36, v35
	ds_read_b128 v[32:35], v68 offset:576
	ds_read_b128 v[88:91], v68 offset:2624
	v_fmac_f32_e32 v98, v94, v38
	v_fmac_f32_e32 v98, v95, v78
	ds_read_b128 v[92:95], v68 offset:4672
	s_waitcnt lgkmcnt(1)
	v_mul_f32_e32 v87, v79, v88
	v_fmac_f32_e32 v87, v44, v32
	v_mul_f32_e32 v44, v79, v89
	s_waitcnt lgkmcnt(0)
	v_fmac_f32_e32 v98, v92, v87
	v_fmac_f32_e32 v44, v39, v33
	v_mul_f32_e32 v88, v79, v90
	v_mul_f32_e32 v89, v79, v91
	v_fmac_f32_e32 v98, v93, v44
	v_fmac_f32_e32 v88, v40, v34
	v_fmac_f32_e32 v89, v41, v35
	ds_read_b128 v[32:35], v68 offset:592
	ds_read_b128 v[90:93], v68 offset:2640
	v_fmac_f32_e32 v98, v94, v88
	v_fmac_f32_e32 v98, v95, v89
	ds_read_b128 v[94:97], v68 offset:4688
	s_waitcnt lgkmcnt(1)
	v_mul_f32_e32 v90, v79, v90
	v_fmac_f32_e32 v90, v45, v32
	v_mul_f32_e32 v39, v79, v91
	s_waitcnt lgkmcnt(0)
	v_fmac_f32_e32 v98, v94, v90
	v_fmac_f32_e32 v39, v42, v33
	v_mul_f32_e32 v40, v79, v92
	v_mul_f32_e32 v45, v79, v93
	v_fmac_f32_e32 v98, v95, v39
	v_fmac_f32_e32 v40, v43, v34
	v_fmac_f32_e32 v45, v46, v35
	ds_read_b128 v[32:35], v68 offset:608
	ds_read_b128 v[92:95], v68 offset:2656
	v_fmac_f32_e32 v98, v96, v40
	v_fmac_f32_e32 v98, v97, v45
	ds_read_b128 v[104:107], v68 offset:4704
	s_waitcnt lgkmcnt(1)
	v_mul_f32_e32 v46, v79, v92
	v_fmac_f32_e32 v46, v47, v32
	v_mul_f32_e32 v47, v79, v93
	v_mul_f32_e32 v91, v79, v94
	v_mul_f32_e32 v92, v79, v95
	v_fmac_f32_e32 v47, v99, v33
	v_fmac_f32_e32 v91, v100, v34
	v_fmac_f32_e32 v92, v101, v35
	ds_read_b128 v[32:35], v68 offset:624
	ds_read_b128 v[94:97], v68 offset:2672
	s_waitcnt lgkmcnt(2)
	v_fmac_f32_e32 v98, v104, v46
	v_fmac_f32_e32 v98, v105, v47
	v_fmac_f32_e32 v98, v106, v91
	v_fmac_f32_e32 v98, v107, v92
	s_waitcnt lgkmcnt(0)
	v_mul_f32_e32 v93, v79, v94
	v_fmac_f32_e32 v93, v102, v32
	ds_read_b128 v[100:103], v68 offset:4720
	v_mul_f32_e32 v41, v79, v95
	v_fmac_f32_e32 v41, v51, v33
	v_mul_f32_e32 v42, v79, v96
	v_fmac_f32_e32 v42, v52, v34
	s_waitcnt lgkmcnt(0)
	v_fmac_f32_e32 v98, v100, v93
	v_fmac_f32_e32 v98, v101, v41
	v_mul_f32_e32 v43, v79, v97
	v_fmac_f32_e32 v98, v102, v42
	v_fmac_f32_e32 v43, v53, v35
	v_fmac_f32_e32 v98, v103, v43
	ds_write_b32 v86, v98 offset:8704
	ds_read2st64_b32 v[36:37], v82 offset0:28 offset1:30
	ds_read_b128 v[94:97], v68 offset:1024
	ds_read_b128 v[98:101], v68 offset:1040
	ds_read_b128 v[102:105], v68 offset:1056
	ds_read_b128 v[32:35], v68 offset:1072
	ds_read_b128 v[106:109], v68 offset:3072
	ds_read_b128 v[110:113], v68 offset:5120
	s_waitcnt lgkmcnt(1)
	v_mul_f32_e32 v52, v36, v106
	v_mul_f32_e32 v53, v36, v107
	v_fmac_f32_e32 v52, v54, v94
	v_fmac_f32_e32 v53, v55, v95
	v_mul_f32_e32 v54, v36, v108
	v_mul_f32_e32 v55, v36, v109
	ds_read_b128 v[106:109], v68 offset:3088
	s_waitcnt lgkmcnt(1)
	v_fma_f32 v94, v110, v52, 0
	v_fmac_f32_e32 v94, v111, v53
	v_fmac_f32_e32 v54, v56, v96
	v_fmac_f32_e32 v94, v112, v54
	v_fmac_f32_e32 v55, v57, v97
	s_waitcnt lgkmcnt(0)
	v_mul_f32_e32 v56, v36, v106
	v_mul_f32_e32 v51, v36, v107
	v_fmac_f32_e32 v94, v113, v55
	v_fmac_f32_e32 v56, v58, v98
	ds_read_b128 v[110:113], v68 offset:5136
	v_fmac_f32_e32 v51, v48, v99
	ds_read_b128 v[96:99], v68 offset:3104
	v_mul_f32_e32 v48, v36, v108
	v_mul_f32_e32 v57, v36, v109
	ds_read_b128 v[106:109], v68 offset:5152
	s_waitcnt lgkmcnt(2)
	v_fmac_f32_e32 v94, v110, v56
	v_fmac_f32_e32 v57, v59, v101
	s_waitcnt lgkmcnt(1)
	v_mul_f32_e32 v58, v36, v96
	v_mul_f32_e32 v59, v36, v97
	v_fmac_f32_e32 v94, v111, v51
	v_fmac_f32_e32 v48, v49, v100
	v_fmac_f32_e32 v58, v60, v102
	v_fmac_f32_e32 v59, v61, v103
	v_mul_f32_e32 v60, v36, v98
	v_mul_f32_e32 v61, v36, v99
	ds_read_b128 v[96:99], v68 offset:3120
	v_fmac_f32_e32 v94, v112, v48
	v_fmac_f32_e32 v94, v113, v57
	ds_read_b128 v[100:103], v68 offset:5168
	s_waitcnt lgkmcnt(2)
	v_fmac_f32_e32 v94, v106, v58
	v_fmac_f32_e32 v94, v107, v59
	v_fmac_f32_e32 v60, v62, v104
	v_fmac_f32_e32 v94, v108, v60
	v_fmac_f32_e32 v61, v63, v105
	s_waitcnt lgkmcnt(1)
	v_mul_f32_e32 v62, v36, v96
	v_fmac_f32_e32 v94, v109, v61
	v_fmac_f32_e32 v62, v76, v32
	v_mul_f32_e32 v49, v36, v97
	s_waitcnt lgkmcnt(0)
	v_fmac_f32_e32 v94, v100, v62
	v_fmac_f32_e32 v49, v50, v33
	v_mul_f32_e32 v50, v36, v98
	v_mul_f32_e32 v63, v36, v99
	v_fmac_f32_e32 v94, v101, v49
	v_fmac_f32_e32 v50, v38, v34
	v_fmac_f32_e32 v63, v78, v35
	ds_read_b128 v[32:35], v68 offset:1088
	ds_read_b128 v[96:99], v68 offset:3136
	v_fmac_f32_e32 v94, v102, v50
	v_fmac_f32_e32 v94, v103, v63
	ds_read_b128 v[100:103], v68 offset:5184
	s_waitcnt lgkmcnt(1)
	v_mul_f32_e32 v76, v36, v96
	v_fmac_f32_e32 v76, v87, v32
	v_mul_f32_e32 v78, v36, v97
	s_waitcnt lgkmcnt(0)
	v_fmac_f32_e32 v94, v100, v76
	v_fmac_f32_e32 v78, v44, v33
	v_mul_f32_e32 v44, v36, v98
	v_mul_f32_e32 v79, v36, v99
	v_fmac_f32_e32 v94, v101, v78
	v_fmac_f32_e32 v44, v88, v34
	v_fmac_f32_e32 v79, v89, v35
	ds_read_b128 v[32:35], v68 offset:1104
	ds_read_b128 v[96:99], v68 offset:3152
	v_fmac_f32_e32 v94, v102, v44
	v_fmac_f32_e32 v94, v103, v79
	ds_read_b128 v[100:103], v68 offset:5200
	s_waitcnt lgkmcnt(1)
	v_mul_f32_e32 v87, v36, v96
	v_fmac_f32_e32 v87, v90, v32
	v_mul_f32_e32 v38, v36, v97
	s_waitcnt lgkmcnt(0)
	v_fmac_f32_e32 v94, v100, v87
	v_fmac_f32_e32 v38, v39, v33
	v_mul_f32_e32 v39, v36, v98
	v_mul_f32_e32 v88, v36, v99
	v_fmac_f32_e32 v94, v101, v38
	v_fmac_f32_e32 v39, v40, v34
	v_fmac_f32_e32 v88, v45, v35
	ds_read_b128 v[32:35], v68 offset:1120
	ds_read_b128 v[96:99], v68 offset:3168
	v_fmac_f32_e32 v94, v102, v39
	v_fmac_f32_e32 v94, v103, v88
	ds_read_b128 v[100:103], v68 offset:5216
	s_waitcnt lgkmcnt(1)
	v_mul_f32_e32 v45, v36, v96
	v_fmac_f32_e32 v45, v46, v32
	v_mul_f32_e32 v46, v36, v97
	s_waitcnt lgkmcnt(0)
	v_fmac_f32_e32 v94, v100, v45
	v_fmac_f32_e32 v46, v47, v33
	v_mul_f32_e32 v47, v36, v98
	v_mul_f32_e32 v89, v36, v99
	v_fmac_f32_e32 v94, v101, v46
	v_fmac_f32_e32 v47, v91, v34
	v_fmac_f32_e32 v89, v92, v35
	ds_read_b128 v[32:35], v68 offset:1136
	ds_read_b128 v[96:99], v68 offset:3184
	v_fmac_f32_e32 v94, v102, v47
	v_fmac_f32_e32 v94, v103, v89
	ds_read_b128 v[100:103], v68 offset:5232
	s_waitcnt lgkmcnt(1)
	v_mul_f32_e32 v90, v36, v96
	v_fmac_f32_e32 v90, v93, v32
	v_mul_f32_e32 v40, v36, v97
	s_waitcnt lgkmcnt(0)
	v_fmac_f32_e32 v94, v100, v90
	v_fmac_f32_e32 v40, v41, v33
	v_mul_f32_e32 v41, v36, v98
	v_fmac_f32_e32 v94, v101, v40
	v_fmac_f32_e32 v41, v42, v34
	v_mul_f32_e32 v36, v36, v99
	v_fmac_f32_e32 v94, v102, v41
	v_fmac_f32_e32 v36, v43, v35
	v_fmac_f32_e32 v94, v103, v36
	ds_write_b32 v86, v94 offset:9216
	ds_read_b128 v[92:95], v68 offset:1536
	ds_read_b128 v[96:99], v68 offset:1552
	ds_read_b128 v[100:103], v68 offset:1568
	ds_read_b128 v[32:35], v68 offset:1584
	ds_read_b128 v[104:107], v68 offset:3584
	ds_read_b128 v[108:111], v68 offset:5632
	s_waitcnt lgkmcnt(1)
	v_mul_f32_e32 v42, v37, v104
	v_mul_f32_e32 v43, v37, v105
	v_fmac_f32_e32 v42, v52, v92
	v_fmac_f32_e32 v43, v53, v93
	v_mul_f32_e32 v52, v37, v106
	v_mul_f32_e32 v53, v37, v107
	v_fmac_f32_e32 v52, v54, v94
	v_fmac_f32_e32 v53, v55, v95
	ds_read_b128 v[92:95], v68 offset:3600
	ds_read_b128 v[104:107], v68 offset:5648
	s_waitcnt lgkmcnt(2)
	v_fma_f32 v91, v108, v42, 0
	v_fmac_f32_e32 v91, v109, v43
	v_fmac_f32_e32 v91, v110, v52
	s_waitcnt lgkmcnt(1)
	v_mul_f32_e32 v55, v37, v93
	v_fmac_f32_e32 v55, v51, v97
	v_mul_f32_e32 v51, v37, v94
	v_mul_f32_e32 v54, v37, v92
	v_fmac_f32_e32 v51, v48, v98
	v_mul_f32_e32 v48, v37, v95
	ds_read_b128 v[92:95], v68 offset:3616
	v_fmac_f32_e32 v91, v111, v53
	v_fmac_f32_e32 v54, v56, v96
	v_fmac_f32_e32 v48, v57, v99
	ds_read_b128 v[96:99], v68 offset:5664
	s_waitcnt lgkmcnt(2)
	v_fmac_f32_e32 v91, v104, v54
	v_fmac_f32_e32 v91, v105, v55
	v_fmac_f32_e32 v91, v106, v51
	s_waitcnt lgkmcnt(1)
	v_mul_f32_e32 v56, v37, v92
	v_fmac_f32_e32 v91, v107, v48
	v_fmac_f32_e32 v56, v58, v100
	v_mul_f32_e32 v57, v37, v93
	s_waitcnt lgkmcnt(0)
	v_fmac_f32_e32 v91, v96, v56
	v_fmac_f32_e32 v57, v59, v101
	v_fmac_f32_e32 v91, v97, v57
	v_mul_f32_e32 v96, v37, v94
	v_mul_f32_e32 v97, v37, v95
	v_fmac_f32_e32 v96, v60, v102
	v_fmac_f32_e32 v97, v61, v103
	ds_read_b128 v[58:61], v68 offset:3632
	ds_read_b128 v[92:95], v68 offset:5680
	v_fmac_f32_e32 v91, v98, v96
	v_fmac_f32_e32 v91, v99, v97
	s_waitcnt lgkmcnt(1)
	v_mul_f32_e32 v98, v37, v58
	v_fmac_f32_e32 v98, v62, v32
	v_mul_f32_e32 v62, v37, v59
	v_fmac_f32_e32 v62, v49, v33
	v_mul_f32_e32 v49, v37, v60
	v_fmac_f32_e32 v49, v50, v34
	v_mul_f32_e32 v50, v37, v61
	s_waitcnt lgkmcnt(0)
	v_fmac_f32_e32 v91, v92, v98
	v_fmac_f32_e32 v50, v63, v35
	ds_read_b128 v[32:35], v68 offset:1600
	ds_read_b128 v[58:61], v68 offset:3648
	v_fmac_f32_e32 v91, v93, v62
	v_fmac_f32_e32 v91, v94, v49
	v_fmac_f32_e32 v91, v95, v50
	ds_read_b128 v[92:95], v68 offset:5696
	s_waitcnt lgkmcnt(1)
	v_mul_f32_e32 v63, v37, v58
	v_fmac_f32_e32 v63, v76, v32
	v_mul_f32_e32 v76, v37, v59
	v_fmac_f32_e32 v76, v78, v33
	v_mul_f32_e32 v78, v37, v60
	v_mul_f32_e32 v99, v37, v61
	s_waitcnt lgkmcnt(0)
	v_fmac_f32_e32 v91, v92, v63
	v_fmac_f32_e32 v78, v44, v34
	v_fmac_f32_e32 v99, v79, v35
	ds_read_b128 v[32:35], v68 offset:1616
	ds_read_b128 v[58:61], v68 offset:3664
	v_fmac_f32_e32 v91, v93, v76
	v_fmac_f32_e32 v91, v94, v78
	v_fmac_f32_e32 v91, v95, v99
	ds_read_b128 v[92:95], v68 offset:5712
	s_waitcnt lgkmcnt(1)
	v_mul_f32_e32 v79, v37, v58
	v_fmac_f32_e32 v79, v87, v32
	v_mul_f32_e32 v87, v37, v59
	v_fmac_f32_e32 v87, v38, v33
	v_mul_f32_e32 v38, v37, v60
	s_waitcnt lgkmcnt(0)
	v_fmac_f32_e32 v91, v92, v79
	v_fmac_f32_e32 v38, v39, v34
	v_mul_f32_e32 v39, v37, v61
	v_fmac_f32_e32 v91, v93, v87
	v_fmac_f32_e32 v39, v88, v35
	ds_read_b128 v[32:35], v68 offset:1632
	ds_read_b128 v[58:61], v68 offset:3680
	v_fmac_f32_e32 v91, v94, v38
	v_fmac_f32_e32 v91, v95, v39
	ds_read_b128 v[92:95], v68 offset:5728
	s_waitcnt lgkmcnt(1)
	v_mul_f32_e32 v88, v37, v58
	v_fmac_f32_e32 v88, v45, v32
	s_waitcnt lgkmcnt(0)
	v_fmac_f32_e32 v91, v92, v88
	v_mul_f32_e32 v92, v37, v59
	v_fmac_f32_e32 v92, v46, v33
	v_fmac_f32_e32 v91, v93, v92
	v_mul_f32_e32 v93, v37, v60
	v_fmac_f32_e32 v93, v47, v34
	v_fmac_f32_e32 v91, v94, v93
	v_mul_f32_e32 v94, v37, v61
	v_fmac_f32_e32 v94, v89, v35
	ds_read_b128 v[32:35], v68 offset:1648
	ds_read_b128 v[44:47], v68 offset:3696
	ds_read_b128 v[58:61], v68 offset:5744
	v_fmac_f32_e32 v91, v95, v94
	s_waitcnt lgkmcnt(1)
	v_mul_f32_e32 v44, v37, v44
	v_mul_f32_e32 v45, v37, v45
	v_fmac_f32_e32 v44, v90, v32
	v_fmac_f32_e32 v45, v40, v33
	v_mul_f32_e32 v40, v37, v46
	v_lshl_add_u64 v[32:33], v[70:71], 0, s[8:9]
	s_waitcnt lgkmcnt(0)
	v_fmac_f32_e32 v91, v58, v44
	v_fmac_f32_e32 v40, v41, v34
	v_mul_f32_e32 v41, v37, v47
	v_add_co_u32_e32 v34, vcc, s13, v32
	v_fmac_f32_e32 v91, v59, v45
	v_fmac_f32_e32 v41, v36, v35
	v_addc_co_u32_e32 v35, vcc, 0, v33, vcc
	v_fmac_f32_e32 v91, v60, v40
	v_add_co_u32_e32 v36, vcc, s70, v32
	v_fmac_f32_e32 v91, v61, v41
	s_nop 0
	v_addc_co_u32_e32 v37, vcc, 0, v33, vcc
	s_movk_i32 s8, 0x3000
	ds_write_b32 v86, v91 offset:9728
	global_store_dword v[32:33], v42, off nt
	global_store_dword v[32:33], v43, off offset:512 nt
	global_store_dword v[32:33], v52, off offset:1024 nt
	global_store_dword v[32:33], v53, off offset:1536 nt
	global_store_dword v[32:33], v54, off offset:2048 nt
	global_store_dword v[32:33], v55, off offset:2560 nt
	global_store_dword v[32:33], v51, off offset:3072 nt
	global_store_dword v[32:33], v48, off offset:3584 nt
	v_add_co_u32_e32 v32, vcc, s8, v32
	global_store_dword v[36:37], v56, off offset:-4096 nt
	global_store_dword v[34:35], v57, off offset:512 nt
	global_store_dword v[34:35], v96, off offset:1024 nt
	global_store_dword v[34:35], v97, off offset:1536 nt
	global_store_dword v[34:35], v98, off offset:2048 nt
	global_store_dword v[34:35], v62, off offset:2560 nt
	global_store_dword v[34:35], v49, off offset:3072 nt
	global_store_dword v[34:35], v50, off offset:3584 nt
	global_store_dword v[36:37], v63, off nt
	global_store_dword v[36:37], v76, off offset:512 nt
	global_store_dword v[36:37], v78, off offset:1024 nt
	global_store_dword v[36:37], v99, off offset:1536 nt
	global_store_dword v[36:37], v79, off offset:2048 nt
	global_store_dword v[36:37], v87, off offset:2560 nt
	global_store_dword v[36:37], v38, off offset:3072 nt
	global_store_dword v[36:37], v39, off offset:3584 nt
	v_addc_co_u32_e32 v33, vcc, 0, v33, vcc
	global_store_dword v[32:33], v88, off nt
	global_store_dword v[32:33], v92, off offset:512 nt
	global_store_dword v[32:33], v93, off offset:1024 nt
	global_store_dword v[32:33], v94, off offset:1536 nt
	global_store_dword v[32:33], v44, off offset:2048 nt
	global_store_dword v[32:33], v45, off offset:2560 nt
	global_store_dword v[32:33], v40, off offset:3072 nt
	global_store_dword v[32:33], v41, off offset:3584 nt
	s_waitcnt lgkmcnt(0)
	s_barrier
	ds_read_b32 v34, v84 offset:8192
	ds_read2st64_b32 v[32:33], v85 offset0:40 offset1:48
	s_waitcnt lgkmcnt(0)
	v_add_f32_e32 v32, v34, v32
	ds_read_b32 v34, v85 offset:14336
	s_waitcnt lgkmcnt(0)
	v_add_f32_e32 v33, v33, v34
	v_add_f32_e32 v32, v32, v33
	v_mul_f32_e32 v33, v32, v32
	ds_bpermute_b32 v33, v215, v33
	s_waitcnt lgkmcnt(0)
	v_fmac_f32_e32 v33, v32, v32
	ds_bpermute_b32 v34, v236, v33
	s_waitcnt lgkmcnt(0)
	v_add_f32_e32 v33, v33, v34
	ds_bpermute_b32 v34, v237, v33
	s_waitcnt lgkmcnt(0)
	v_add_f32_e32 v33, v33, v34
	ds_bpermute_b32 v34, v238, v33
	s_waitcnt lgkmcnt(0)
	v_add_f32_e32 v33, v33, v34
	ds_bpermute_b32 v34, v233, v33
	s_waitcnt lgkmcnt(0)
	v_add_f32_e32 v33, v33, v34
	ds_bpermute_b32 v34, v234, v33
	s_and_saveexec_b64 s[8:9], s[36:37]
	s_cbranch_execz .LBB0_559
	s_waitcnt lgkmcnt(0)
	v_add_f32_e32 v33, v33, v34
	ds_write_b32 v73, v33 offset:16384
	s_branch .LBB0_559
